# SSD acs/dtl vectors stored by pass 1 (f32, spare workspace) and loaded by pass 2 instead of being recomputed by waves 0-1
# speedup vs baseline: 1.0119x; 1.0094x over previous
; #define LAS __attribute__((address_space(3)))
; DI float bperm(float v, int srclane) { return __int_as_float(__builtin_amdgcn_ds_bpermute(srclane << 2, __float_as_int(v))); }
; DI float softplus_f(float x) { return x > 20.f ? x : log1pf(__expf(x)); }
; DI void ssd_acs(const float* DT, const LayerP& P, int row0, int h, LAS float* acs, LAS float* dtl, int lane) {
;     const float bias = P.ssd_dtb[h], A = -__expf(P.ssd_alog[h]);
;     const float d0 = softplus_f(DT[(size_t)(row0 + 2 * lane) * 4 + h] + bias), d1 = softplus_f(DT[(size_t)(row0 + 2 * lane + 1) * 4 + h] + bias);
;     const float a0 = d0 * A, a1 = d1 * A; float incl = a0 + a1;
; #pragma unroll
;     for (int o = 1; o < 64; o <<= 1) { const float t = bperm(incl, lane - o); if (lane >= o) incl += t; }
;     const float excl = incl - (a0 + a1);
;     acs[2 * lane] = excl + a0; acs[2 * lane + 1] = incl; dtl[2 * lane] = d0; dtl[2 * lane + 1] = d1;
; }
; DI void ssd_pass1(LAS unsigned char* lds, const Args& a, const LayerP& P, int unit, int wv) {
;     ...
;     if (wave < 4) ssd_acs((const float*)(a.ws + WS_DT), P, row0, wave, acs + wave * 128, dtl + wave * 128, lane);
.LBB0_991:
	s_or_b64 exec, exec, s[2:3]
	v_mul_f32_e32 v116, 0x3fb8aa3b, v117
	v_exp_f32_e32 v116, v116
	v_cmp_eq_u32_e32 vcc, 0, v119
	v_lshlrev_b32_e32 v0, 2, v0
	v_readlane_b32 s2, v254, 6
	v_mul_f32_e32 v117, v116, v115
	v_fma_f32 v120, v114, -v116, -v117
	v_lshlrev_b32_e32 v117, 2, v119
	v_add_u32_e32 v121, -4, v117
	ds_bpermute_b32 v121, v121, v120
	v_add_u32_e32 v122, -8, v117
	s_waitcnt lgkmcnt(0)
	v_add_f32_e32 v121, v120, v121
	v_cndmask_b32_e32 v121, v121, v120, vcc
	ds_bpermute_b32 v122, v122, v121
	v_cmp_gt_u32_e32 vcc, 2, v119
	s_waitcnt lgkmcnt(0)
	v_add_f32_e32 v122, v121, v122
	v_cndmask_b32_e32 v121, v122, v121, vcc
	v_add_u32_e32 v122, -16, v117
	ds_bpermute_b32 v122, v122, v121
	v_cmp_gt_u32_e32 vcc, 4, v119
	s_waitcnt lgkmcnt(0)
	v_add_f32_e32 v122, v121, v122
	v_cndmask_b32_e32 v121, v122, v121, vcc
	v_subrev_u32_e32 v122, 32, v117
	ds_bpermute_b32 v122, v122, v121
	v_cmp_gt_u32_e32 vcc, 8, v119
	s_waitcnt lgkmcnt(0)
	v_add_f32_e32 v122, v121, v122
	v_cndmask_b32_e32 v121, v122, v121, vcc
	v_subrev_u32_e32 v122, 64, v117
	ds_bpermute_b32 v122, v122, v121
	v_cmp_gt_u32_e32 vcc, 16, v119
	v_add_u32_e32 v117, 0xffffff80, v117
	s_waitcnt lgkmcnt(0)
	v_add_f32_e32 v122, v121, v122
	v_cndmask_b32_e32 v121, v122, v121, vcc
	ds_bpermute_b32 v117, v117, v121
	v_cmp_gt_u32_e32 vcc, 32, v119
	s_waitcnt lgkmcnt(0)
	v_add_f32_e32 v117, v121, v117
	v_cndmask_b32_e32 v117, v117, v121, vcc
	v_sub_f32_e32 v119, v117, v120
	v_fma_f32 v116, v114, -v116, v119
	s_lshl_b32 s32, s34, 2
	s_add_i32 s32, s32, s77
	s_lshl_b32 s32, s32, 10
	s_add_u32 s96, s38, 0x1b000000
	s_addc_u32 s97, s39, 0
	v_add_u32_e32 v219, s32, v0
	global_store_dwordx2 v219, v[116:117], s[96:97]
	global_store_dwordx2 v219, v[114:115], s[96:97] offset:512
	v_add_u32_e32 v119, s88, v0
	v_add_u32_e32 v0, s2, v0
	ds_write_b64 v119, v[116:117]
	ds_write_b64 v0, v[114:115]

; __device__ __forceinline__ int ltid(int wv) { int l; asm volatile("v_mbcnt_lo_u32_b32 %0, -1, 0\n\tv_mbcnt_hi_u32_b32 %0, -1, %0" : "=v"(l)); asm volatile("" : "+s"(wv)); return (wv << 6) | l; }
; #define LAS __attribute__((address_space(3)))
; DI float bperm(float v, int srclane) { return __int_as_float(__builtin_amdgcn_ds_bpermute(srclane << 2, __float_as_int(v))); }
; DI float softplus_f(float x) { return x > 20.f ? x : log1pf(__expf(x)); }
; DI void ssd_acs(const float* DT, const LayerP& P, int row0, int h, LAS float* acs, LAS float* dtl, int lane) {
;     const float bias = P.ssd_dtb[h], A = -__expf(P.ssd_alog[h]);
;     const float d0 = softplus_f(DT[(size_t)(row0 + 2 * lane) * 4 + h] + bias), d1 = softplus_f(DT[(size_t)(row0 + 2 * lane + 1) * 4 + h] + bias);
;     const float a0 = d0 * A, a1 = d1 * A; float incl = a0 + a1;
; #pragma unroll
;     for (int o = 1; o < 64; o <<= 1) { const float t = bperm(incl, lane - o); if (lane >= o) incl += t; }
;     const float excl = incl - (a0 + a1);
;     acs[2 * lane] = excl + a0; acs[2 * lane + 1] = incl; dtl[2 * lane] = d0; dtl[2 * lane + 1] = d1;
; }
; DI void ssd_pass2(LAS unsigned char* lds, const Args& a, const LayerP& P, int unit, int wv) {
;     ...
;         const int tid = ltid(wv), lane = tid & 63, cv = tid & 15, t0 = (tid >> 4) * 4, r = lane & 15, q = lane >> 4;
;         __syncthreads();
;         if (wave < 2) ssd_acs((const float*)(a.ws + WS_DT), P, row0, 2 * g + wave, acs + wave * 128, dtl + wave * 128, lane);
.LBB0_1367:
	v_readlane_b32 s2, v254, 9
	v_readlane_b32 s3, v254, 10
	v_mbcnt_lo_u32_b32 v119, -1, 0
	v_mbcnt_hi_u32_b32 v119, -1, v119
	s_mov_b32 s16, s77
	v_and_b32_e32 v118, 63, v119
	s_andn2_b64 vcc, exec, s[2:3]
	s_barrier
	s_cbranch_vccnz .LBB0_1373
	s_lshl_b32 s2, s15, 1
	s_or_b32 s58, s2, s77
	s_lshl_b32 s3, s34, 2
	s_add_i32 s2, s58, s3
	s_lshl_b32 s2, s2, 10
	s_add_u32 s98, s38, 0x1b000000
	s_addc_u32 s99, s39, 0
	v_lshlrev_b32_e32 v166, 3, v118
	v_add_u32_e32 v167, s2, v166
	global_load_dwordx2 v[160:161], v167, s[98:99]
	global_load_dwordx2 v[162:163], v167, s[98:99] offset:512
	v_readlane_b32 s2, v254, 11
	v_add_u32_e32 v164, s88, v166
	s_nop 1
	v_add_u32_e32 v165, s2, v166

; #define LAS __attribute__((address_space(3)))
; DI u32x4 pack8(const float (&v)[8]) { u32x4 w; w.x = pk2(v[0], v[1]); w.y = pk2(v[2], v[3]); w.z = pk2(v[4], v[5]); w.w = pk2(v[6], v[7]); return w; }
; DI void ssd_pass2(LAS unsigned char* lds, const Args& a, const LayerP& P, int unit, int wv) {
;     ...
;         if (wave < 2) ssd_acs((const float*)(a.ws + WS_DT), P, row0, 2 * g + wave, acs + wave * 128, dtl + wave * 128, lane);
;         { float o[4][8]; conv8x4<true>(Hb + C_XBC + 512 + g * 128 + cv * 8, c * 128 + t0, P.ssd_cw + 512 + g * 128 + cv * 8, 768, P.ssd_cb + 512 + g * 128 + cv * 8, o);
; #pragma unroll
;           for (int t = 0; t < 4; ++t) *(LAS u32x4*)(Cm + (t0 + t) * PT + cv * 8) = pack8(o[t]); }
;         { const bf16_t* ST = (const bf16_t*)((const unsigned char*)a.out + DO_ST) + ((size_t)((b * NCH + c) * 4 + 2 * g)) * 8192;
; #pragma unroll
;           for (int i = 0; i < 4; ++i) { const int e8 = (i * 512 + tid) * 8; *(LAS u32x4*)(R1 + (e8 >> 7) * PT + (e8 & 127)) = *(const u32x4*)(ST + e8); } }
.LBB0_1387:
	s_or_b64 exec, exec, s[2:3]
	s_lshl_b64 s[2:3], s[58:59], 2
	v_lshlrev_b32_e32 v122, 3, v120
	s_add_u32 s36, s40, s2
	s_addc_u32 s37, s41, s3
	v_lshlrev_b32_e32 v0, 2, v122
	v_lshl_add_u64 v[102:103], s[36:37], 0, v[0:1]
	s_mov_b64 s[94:95], 0x800
	v_lshl_add_u64 v[14:15], v[102:103], 0, s[94:95]
	s_add_u32 s94, s42, s2
	s_addc_u32 s95, s43, s3
	s_mov_b64 s[2:3], 0x2000
	global_load_dwordx4 v[6:9], v0, s[36:37] offset:2064
	global_load_dwordx4 v[30:33], v0, s[36:37] offset:2048
	global_load_dwordx4 v[10:13], v[14:15], off offset:3088
	global_load_dwordx4 v[36:39], v[14:15], off offset:3072
	v_lshl_add_u64 v[14:15], v[102:103], 0, s[2:3]
	s_movk_i32 s2, 0x2000
	v_add_co_u32_e32 v104, vcc, s2, v102
	s_mov_b64 s[2:3], 0x2c00
	s_nop 0
	v_addc_co_u32_e32 v105, vcc, 0, v103, vcc
	v_lshl_add_u64 v[18:19], v[102:103], 0, s[2:3]
	global_load_dwordx4 v[40:43], v[104:105], off
	s_nop 0
	global_load_dwordx4 v[14:17], v[14:15], off offset:16
	s_nop 0
	global_load_dwordx4 v[44:47], v[104:105], off offset:3072
	s_nop 0
	global_load_dwordx4 v[18:21], v[18:19], off offset:16
	s_nop 0
	global_load_dwordx4 v[22:25], v0, s[94:95] offset:2064
	global_load_dwordx4 v[48:51], v0, s[94:95] offset:2048
	s_waitcnt vmcnt(10)
	v_lshlrev_b32_e32 v72, 16, v60
	v_and_b32_e32 v73, 0xffff0000, v60
	v_lshlrev_b32_e32 v82, 16, v56
	v_and_b32_e32 v83, 0xffff0000, v56
	v_lshlrev_b32_e32 v76, 16, v68
	v_and_b32_e32 v77, 0xffff0000, v68
	v_lshlrev_b32_e32 v74, 16, v64
	v_and_b32_e32 v75, 0xffff0000, v64
	v_lshlrev_b32_e32 v80, 16, v61
	v_and_b32_e32 v81, 0xffff0000, v61
	v_lshlrev_b32_e32 v84, 16, v57
	v_and_b32_e32 v85, 0xffff0000, v57
	v_lshlrev_b32_e32 v60, 16, v65
	v_and_b32_e32 v61, 0xffff0000, v65
	v_lshlrev_b32_e32 v86, 16, v58
	v_and_b32_e32 v87, 0xffff0000, v58
	v_lshlrev_b32_e32 v68, 16, v66
	v_lshlrev_b32_e32 v92, 16, v59
	v_and_b32_e32 v93, 0xffff0000, v59
	v_and_b32_e32 v59, 0xffff0000, v67
	v_lshlrev_b32_e32 v90, 16, v54
	v_and_b32_e32 v91, 0xffff0000, v54
	s_lshl_b32 s58, s15, 1
	s_or_b32 s2, s58, s12
	s_ashr_i32 s3, s2, 31
	s_lshl_b64 s[2:3], s[2:3], 14
	s_add_u32 s2, s46, s2
	s_addc_u32 s3, s47, s3
	s_waitcnt vmcnt(0)
	s_cmp_lt_u32 s77, 2
	s_cbranch_scc0 .Lmy_acs_skip
	ds_write_b64 v164, v[160:161]
	ds_write_b64 v165, v[162:163]
.Lmy_acs_skip:
	v_pk_fma_f32 v[72:73], v[30:31], v[72:73], v[48:49]
	s_nop 0
	v_pk_fma_f32 v[72:73], v[36:37], v[82:83], v[72:73]
	s_nop 0
	v_pk_fma_f32 v[72:73], v[40:41], v[76:77], v[72:73]
	s_nop 0
	v_pk_fma_f32 v[72:73], v[44:45], v[74:75], v[72:73]
	s_nop 0
	v_mul_f32_e32 v56, 0xbfb8aa3b, v72
	v_exp_f32_e32 v56, v56
	s_nop 0
	v_add_f32_e32 v56, 1.0, v56
	v_rcp_f32_e32 v78, v56
	v_mul_f32_e32 v56, 0xbfb8aa3b, v73
	v_exp_f32_e32 v56, v56
	s_nop 0
	v_add_f32_e32 v56, 1.0, v56
	v_rcp_f32_e32 v79, v56
	v_pk_fma_f32 v[56:57], v[32:33], v[80:81], v[50:51]
	v_lshlrev_b32_e32 v80, 16, v70
	v_pk_fma_f32 v[56:57], v[38:39], v[84:85], v[56:57]
	v_pk_mul_f32 v[72:73], v[72:73], v[78:79]
	v_lshlrev_b32_e32 v78, 16, v69
	v_and_b32_e32 v79, 0xffff0000, v69
	v_pk_fma_f32 v[56:57], v[42:43], v[78:79], v[56:57]
	v_and_b32_e32 v81, 0xffff0000, v70
	v_pk_fma_f32 v[56:57], v[46:47], v[60:61], v[56:57]
	v_and_b32_e32 v69, 0xffff0000, v66
	v_mul_f32_e32 v64, 0xbfb8aa3b, v56
	v_mul_f32_e32 v65, 0xbfb8aa3b, v57
	v_exp_f32_e32 v64, v64
	v_exp_f32_e32 v65, v65
	v_add_f32_e32 v64, 1.0, v64
	v_add_f32_e32 v65, 1.0, v65
	v_rcp_f32_e32 v64, v64
	v_rcp_f32_e32 v65, v65
	s_nop 0
	v_pk_mul_f32 v[56:57], v[56:57], v[64:65]
	v_lshlrev_b32_e32 v64, 16, v62
	v_and_b32_e32 v65, 0xffff0000, v62
	v_pk_fma_f32 v[64:65], v[6:7], v[64:65], v[22:23]
	v_lshlrev_b32_e32 v62, 16, v71
	v_pk_fma_f32 v[64:65], v[10:11], v[86:87], v[64:65]
	s_nop 0
	v_pk_fma_f32 v[64:65], v[14:15], v[80:81], v[64:65]
	s_nop 0
	v_pk_fma_f32 v[64:65], v[18:19], v[68:69], v[64:65]
	s_nop 0
	v_mul_f32_e32 v58, 0xbfb8aa3b, v64
	v_exp_f32_e32 v58, v58
	s_nop 0
	v_add_f32_e32 v58, 1.0, v58
	v_rcp_f32_e32 v88, v58
	v_mul_f32_e32 v58, 0xbfb8aa3b, v65
	v_exp_f32_e32 v58, v58
	s_nop 0
	v_add_f32_e32 v58, 1.0, v58
	v_rcp_f32_e32 v89, v58
	v_lshlrev_b32_e32 v58, 16, v67
	v_pk_mul_f32 v[64:65], v[64:65], v[88:89]
	v_lshlrev_b32_e32 v88, 16, v63
	v_and_b32_e32 v89, 0xffff0000, v63
	v_pk_fma_f32 v[66:67], v[8:9], v[88:89], v[24:25]
	v_and_b32_e32 v63, 0xffff0000, v71
	v_pk_fma_f32 v[66:67], v[12:13], v[92:93], v[66:67]
	v_lshlrev_b32_e32 v88, 16, v52
	v_pk_fma_f32 v[66:67], v[16:17], v[62:63], v[66:67]
	v_and_b32_e32 v89, 0xffff0000, v52
	v_pk_fma_f32 v[66:67], v[20:21], v[58:59], v[66:67]
	s_nop 0
	v_mul_f32_e32 v70, 0xbfb8aa3b, v66
	v_mul_f32_e32 v71, 0xbfb8aa3b, v67
	v_exp_f32_e32 v70, v70
	v_exp_f32_e32 v71, v71
	v_add_f32_e32 v70, 1.0, v70
	v_add_f32_e32 v71, 1.0, v71
	v_rcp_f32_e32 v70, v70
	v_rcp_f32_e32 v71, v71
	s_nop 0
	v_pk_mul_f32 v[66:67], v[66:67], v[70:71]
	v_pk_fma_f32 v[70:71], v[30:31], v[82:83], v[48:49]
	s_nop 0
	v_pk_fma_f32 v[70:71], v[36:37], v[76:77], v[70:71]
	v_pk_fma_f32 v[76:77], v[30:31], v[76:77], v[48:49]
	v_pk_fma_f32 v[70:71], v[40:41], v[74:75], v[70:71]
	v_pk_fma_f32 v[76:77], v[36:37], v[74:75], v[76:77]
	v_pk_fma_f32 v[70:71], v[44:45], v[88:89], v[70:71]
	v_pk_fma_f32 v[76:77], v[40:41], v[88:89], v[76:77]
	v_mul_f32_e32 v52, 0xbfb8aa3b, v70
	v_exp_f32_e32 v52, v52
	v_pk_fma_f32 v[30:31], v[30:31], v[74:75], v[48:49]
	v_add_f32_e32 v52, 1.0, v52
	v_rcp_f32_e32 v82, v52
	v_mul_f32_e32 v52, 0xbfb8aa3b, v71
	v_exp_f32_e32 v52, v52
	v_pk_fma_f32 v[30:31], v[36:37], v[88:89], v[30:31]
	v_add_f32_e32 v52, 1.0, v52
	v_rcp_f32_e32 v83, v52
	s_nop 0
	v_pk_mul_f32 v[70:71], v[70:71], v[82:83]
	v_lshlrev_b32_e32 v82, 16, v53
	v_and_b32_e32 v83, 0xffff0000, v53
; DI float silu_f(float x) { return x * __builtin_amdgcn_rcpf(1.0f + __expf(-x)); }
; template <bool SILU>
; DI void conv_compute(const u32x4 (&raw)[7], const float* w, int C, const float* bias, float (&out)[4][8]) {
;     float wv[4][8], bv[8], x[7][8];
; #pragma unroll
;     for (int j = 0; j < 4; ++j) { const f32x4 a = *(const f32x4*)(w + (size_t)j * C), b = *(const f32x4*)(w + (size_t)j * C + 4);
;         wv[j][0] = a[0]; wv[j][1] = a[1]; wv[j][2] = a[2]; wv[j][3] = a[3]; wv[j][4] = b[0]; wv[j][5] = b[1]; wv[j][6] = b[2]; wv[j][7] = b[3]; }
;     { const f32x4 a = *(const f32x4*)bias, b = *(const f32x4*)(bias + 4); bv[0] = a[0]; bv[1] = a[1]; bv[2] = a[2]; bv[3] = a[3]; bv[4] = b[0]; bv[5] = b[1]; bv[6] = b[2]; bv[7] = b[3]; }
; #pragma unroll
;     for (int i = 0; i < 7; ++i) unpack8(raw[i], x[i]);
; #pragma unroll
;     for (int t = 0; t < 4; ++t)
; #pragma unroll
;         for (int c = 0; c < 8; ++c) { float v = bv[c] + wv[0][c] * x[t][c] + wv[1][c] * x[t + 1][c] + wv[2][c] * x[t + 2][c] + wv[3][c] * x[t + 3][c]; out[t][c] = SILU ? silu_f(v) : v; }
; }
	v_pk_fma_f32 v[52:53], v[32:33], v[84:85], v[50:51]
	s_nop 0
	v_pk_fma_f32 v[52:53], v[38:39], v[78:79], v[52:53]
	v_pk_fma_f32 v[78:79], v[32:33], v[78:79], v[50:51]
	v_pk_fma_f32 v[52:53], v[42:43], v[60:61], v[52:53]
	v_pk_fma_f32 v[78:79], v[38:39], v[60:61], v[78:79]
	v_pk_fma_f32 v[52:53], v[46:47], v[82:83], v[52:53]
	v_pk_fma_f32 v[78:79], v[42:43], v[82:83], v[78:79]
	v_mul_f32_e32 v84, 0xbfb8aa3b, v52
	v_mul_f32_e32 v85, 0xbfb8aa3b, v53
	v_exp_f32_e32 v84, v84
	v_exp_f32_e32 v85, v85
	v_pk_fma_f32 v[32:33], v[32:33], v[60:61], v[50:51]
	v_add_f32_e32 v84, 1.0, v84
	v_add_f32_e32 v85, 1.0, v85
	v_rcp_f32_e32 v84, v84
	v_rcp_f32_e32 v85, v85
	v_pk_fma_f32 v[32:33], v[38:39], v[82:83], v[32:33]
	v_pk_mul_f32 v[52:53], v[52:53], v[84:85]
	v_pk_fma_f32 v[84:85], v[6:7], v[86:87], v[22:23]
	s_nop 0
	v_pk_fma_f32 v[84:85], v[10:11], v[80:81], v[84:85]
	v_pk_fma_f32 v[80:81], v[6:7], v[80:81], v[22:23]
	v_pk_fma_f32 v[84:85], v[14:15], v[68:69], v[84:85]
	v_pk_fma_f32 v[80:81], v[10:11], v[68:69], v[80:81]
	v_pk_fma_f32 v[84:85], v[18:19], v[90:91], v[84:85]
	v_pk_fma_f32 v[80:81], v[14:15], v[90:91], v[80:81]
	v_mul_f32_e32 v54, 0xbfb8aa3b, v84
	v_exp_f32_e32 v54, v54
	v_pk_fma_f32 v[6:7], v[6:7], v[68:69], v[22:23]
	v_add_f32_e32 v54, 1.0, v54
	v_rcp_f32_e32 v86, v54
	v_mul_f32_e32 v54, 0xbfb8aa3b, v85
	v_exp_f32_e32 v54, v54
	v_pk_fma_f32 v[6:7], v[10:11], v[90:91], v[6:7]
	v_lshl_add_u32 v10, v122, 1, 0
	v_mul_lo_u32 v11, v121, s56
	v_add_f32_e32 v54, 1.0, v54
	v_rcp_f32_e32 v87, v54
	v_lshlrev_b32_e32 v54, 16, v55
	v_and_b32_e32 v55, 0xffff0000, v55
	v_add_u32_e32 v132, v10, v11
	v_pk_mul_f32 v[84:85], v[84:85], v[86:87]
	v_pk_fma_f32 v[86:87], v[8:9], v[92:93], v[24:25]
	s_nop 0
	v_pk_fma_f32 v[86:87], v[12:13], v[62:63], v[86:87]
	v_pk_fma_f32 v[62:63], v[8:9], v[62:63], v[24:25]
	v_pk_fma_f32 v[86:87], v[16:17], v[58:59], v[86:87]
	v_pk_fma_f32 v[62:63], v[12:13], v[58:59], v[62:63]
	v_pk_fma_f32 v[86:87], v[20:21], v[54:55], v[86:87]
	v_pk_fma_f32 v[62:63], v[16:17], v[54:55], v[62:63]
	v_mul_f32_e32 v92, 0xbfb8aa3b, v86
	v_mul_f32_e32 v93, 0xbfb8aa3b, v87
	v_exp_f32_e32 v92, v92
	v_exp_f32_e32 v93, v93
	v_add_f32_e32 v92, 1.0, v92
	v_add_f32_e32 v93, 1.0, v93
	v_rcp_f32_e32 v92, v92
	v_rcp_f32_e32 v93, v93
	s_nop 0
	v_pk_mul_f32 v[86:87], v[86:87], v[92:93]
	v_lshlrev_b32_e32 v92, 16, v26
	v_and_b32_e32 v93, 0xffff0000, v26
	v_pk_fma_f32 v[76:77], v[44:45], v[92:93], v[76:77]
	v_pk_fma_f32 v[30:31], v[40:41], v[92:93], v[30:31]
	v_mul_f32_e32 v26, 0xbfb8aa3b, v76
	v_exp_f32_e32 v26, v26
	s_nop 0
	v_add_f32_e32 v26, 1.0, v26
	v_rcp_f32_e32 v96, v26
	v_mul_f32_e32 v26, 0xbfb8aa3b, v77
	v_exp_f32_e32 v26, v26
	s_nop 0
	v_add_f32_e32 v26, 1.0, v26
	v_rcp_f32_e32 v97, v26
	v_lshlrev_b32_e32 v26, 16, v27
	v_and_b32_e32 v27, 0xffff0000, v27
	v_pk_fma_f32 v[78:79], v[46:47], v[26:27], v[78:79]
	v_pk_mul_f32 v[76:77], v[76:77], v[96:97]
	v_mul_f32_e32 v95, 0xbfb8aa3b, v78
	v_exp_f32_e32 v95, v95
	v_pk_fma_f32 v[26:27], v[42:43], v[26:27], v[32:33]
	v_add_f32_e32 v95, 1.0, v95
	v_rcp_f32_e32 v96, v95
	v_mul_f32_e32 v95, 0xbfb8aa3b, v79
	v_exp_f32_e32 v95, v95
	s_nop 0
	v_add_f32_e32 v95, 1.0, v95
	v_rcp_f32_e32 v97, v95
	s_nop 0
	v_pk_mul_f32 v[78:79], v[78:79], v[96:97]
	v_lshlrev_b32_e32 v96, 16, v28
	v_and_b32_e32 v97, 0xffff0000, v28
	v_pk_fma_f32 v[80:81], v[18:19], v[96:97], v[80:81]
	v_pk_fma_f32 v[6:7], v[14:15], v[96:97], v[6:7]
	v_mul_f32_e32 v28, 0xbfb8aa3b, v80
	v_exp_f32_e32 v28, v28
	s_nop 0
	v_add_f32_e32 v28, 1.0, v28
	v_rcp_f32_e32 v98, v28
	v_mul_f32_e32 v28, 0xbfb8aa3b, v81
	v_exp_f32_e32 v28, v28
	s_nop 0
	v_add_f32_e32 v28, 1.0, v28
	v_rcp_f32_e32 v99, v28
	v_lshlrev_b32_e32 v28, 16, v29
	v_and_b32_e32 v29, 0xffff0000, v29
	v_pk_fma_f32 v[62:63], v[20:21], v[28:29], v[62:63]
; #define LAS __attribute__((address_space(3)))
; DI u32x4 pack8(const float (&v)[8]) { u32x4 w; w.x = pk2(v[0], v[1]); w.y = pk2(v[2], v[3]); w.z = pk2(v[4], v[5]); w.w = pk2(v[6], v[7]); return w; }
; DI void ssd_pass2(LAS unsigned char* lds, const Args& a, const LayerP& P, int unit, int wv) {
;     ...
;         { float o[4][8]; conv8x4<true>(Hb + C_XBC + 512 + g * 128 + cv * 8, c * 128 + t0, P.ssd_cw + 512 + g * 128 + cv * 8, 768, P.ssd_cb + 512 + g * 128 + cv * 8, o);
; #pragma unroll
;           for (int t = 0; t < 4; ++t) *(LAS u32x4*)(Cm + (t0 + t) * PT + cv * 8) = pack8(o[t]); }
;         { const bf16_t* ST = (const bf16_t*)((const unsigned char*)a.out + DO_ST) + ((size_t)((b * NCH + c) * 4 + 2 * g)) * 8192;
; #pragma unroll
;           for (int i = 0; i < 4; ++i) { const int e8 = (i * 512 + tid) * 8; *(LAS u32x4*)(R1 + (e8 >> 7) * PT + (e8 & 127)) = *(const u32x4*)(ST + e8); } }
;         u32x4 rawB[7]; conv_load(Hb + C_XBC + 256 + g * 128 + cv * 8, c * 128 + t0, rawB);
	v_pk_mul_f32 v[80:81], v[80:81], v[98:99]
	v_mul_f32_e32 v95, 0xbfb8aa3b, v62
	v_exp_f32_e32 v95, v95
	s_nop 0
	v_add_f32_e32 v95, 1.0, v95
	v_rcp_f32_e32 v98, v95
	v_mul_f32_e32 v95, 0xbfb8aa3b, v63
	v_exp_f32_e32 v95, v95
	s_nop 0
	v_add_f32_e32 v95, 1.0, v95
	v_rcp_f32_e32 v99, v95
	s_nop 0
	v_pk_mul_f32 v[62:63], v[62:63], v[98:99]
	v_lshlrev_b32_e32 v98, 16, v2
	v_and_b32_e32 v99, 0xffff0000, v2
	v_pk_fma_f32 v[30:31], v[44:45], v[98:99], v[30:31]
	s_nop 0
	v_mul_f32_e32 v2, 0xbfb8aa3b, v30
	v_exp_f32_e32 v2, v2
	s_nop 0
	v_add_f32_e32 v2, 1.0, v2
	v_rcp_f32_e32 v36, v2
	v_mul_f32_e32 v2, 0xbfb8aa3b, v31
	v_exp_f32_e32 v2, v2
	s_nop 0
	v_add_f32_e32 v2, 1.0, v2
	v_rcp_f32_e32 v37, v2
	v_lshlrev_b32_e32 v2, 16, v3
	v_and_b32_e32 v3, 0xffff0000, v3
	v_pk_fma_f32 v[2:3], v[46:47], v[2:3], v[26:27]
	v_pk_mul_f32 v[30:31], v[30:31], v[36:37]
	v_mul_f32_e32 v26, 0xbfb8aa3b, v2
	v_mul_f32_e32 v27, 0xbfb8aa3b, v3
	v_exp_f32_e32 v26, v26
	v_exp_f32_e32 v27, v27
	v_mov_b32_e32 v36, 0
	v_mov_b32_e32 v37, 0
	v_add_f32_e32 v26, 1.0, v26
	v_add_f32_e32 v27, 1.0, v27
	v_rcp_f32_e32 v26, v26
	v_rcp_f32_e32 v27, v27
	s_nop 0
	v_pk_mul_f32 v[26:27], v[2:3], v[26:27]
	v_lshlrev_b32_e32 v2, 16, v4
	v_and_b32_e32 v3, 0xffff0000, v4
	v_pk_fma_f32 v[2:3], v[18:19], v[2:3], v[6:7]
	s_nop 0
	v_mul_f32_e32 v4, 0xbfb8aa3b, v2
	v_exp_f32_e32 v4, v4
	s_nop 0
	v_add_f32_e32 v4, 1.0, v4
	v_rcp_f32_e32 v6, v4
	v_mul_f32_e32 v4, 0xbfb8aa3b, v3
	v_exp_f32_e32 v4, v4
	s_nop 0
	v_add_f32_e32 v4, 1.0, v4
	v_rcp_f32_e32 v7, v4
	s_nop 0
	v_pk_mul_f32 v[6:7], v[2:3], v[6:7]
	v_lshlrev_b32_e32 v2, 16, v5
	v_and_b32_e32 v3, 0xffff0000, v5
	v_pk_fma_f32 v[4:5], v[8:9], v[58:59], v[24:25]
	s_nop 0
	v_pk_fma_f32 v[4:5], v[12:13], v[54:55], v[4:5]
	s_nop 0
	v_pk_fma_f32 v[4:5], v[16:17], v[28:29], v[4:5]
	s_nop 0
	v_pk_fma_f32 v[2:3], v[20:21], v[2:3], v[4:5]
	s_nop 0
	v_mul_f32_e32 v4, 0xbfb8aa3b, v2
	v_mul_f32_e32 v5, 0xbfb8aa3b, v3
	v_exp_f32_e32 v4, v4
	v_exp_f32_e32 v5, v5
	v_add_f32_e32 v4, 1.0, v4
	v_add_f32_e32 v5, 1.0, v5
	v_rcp_f32_e32 v4, v4
	v_rcp_f32_e32 v5, v5
	s_nop 0
	v_pk_mul_f32 v[8:9], v[2:3], v[4:5]
	v_cvt_pk_bf16_f32 v2, v72, v73
	v_cvt_pk_bf16_f32 v3, v56, v57
	v_cvt_pk_bf16_f32 v4, v64, v65
	v_cvt_pk_bf16_f32 v5, v66, v67
	ds_write_b128 v132, v[2:5]
	v_cvt_pk_bf16_f32 v2, v70, v71
	v_cvt_pk_bf16_f32 v3, v52, v53
	v_cvt_pk_bf16_f32 v4, v84, v85
	v_cvt_pk_bf16_f32 v5, v86, v87
	ds_write_b128 v132, v[2:5] offset:272
	v_cvt_pk_bf16_f32 v2, v76, v77
	v_cvt_pk_bf16_f32 v3, v78, v79
	v_cvt_pk_bf16_f32 v4, v80, v81
	v_cvt_pk_bf16_f32 v5, v62, v63
	ds_write_b128 v132, v[2:5] offset:544
	v_cvt_pk_bf16_f32 v4, v6, v7
	v_or_b32_e32 v6, 3, v94
	v_mul_lo_u32 v6, v6, s56
	v_cvt_pk_bf16_f32 v2, v30, v31
	v_cvt_pk_bf16_f32 v3, v26, v27
	v_cvt_pk_bf16_f32 v5, v8, v9
	v_add_u32_e32 v133, v10, v6
	ds_write_b128 v133, v[2:5]
	v_lshlrev_b32_e32 v150, 4, v35
	global_load_dwordx4 v[134:137], v150, s[2:3]
	s_add_u32 s2, s2, 0x2000
	s_addc_u32 s3, s3, 0
	global_load_dwordx4 v[138:141], v150, s[2:3]
	s_add_u32 s2, s2, 0x2000
	s_addc_u32 s3, s3, 0
	global_load_dwordx4 v[142:145], v150, s[2:3]
	s_add_u32 s2, s2, 0x2000
	s_addc_u32 s3, s3, 0
	global_load_dwordx4 v[146:149], v150, s[2:3]
	v_and_b32_e32 v6, 0xf0, v150
	v_bfe_i32 v7, v35, 4, 25
	v_mad_u32_u24 v151, v7, s56, v6
	v_mov_b32_e32 v35, 0
	s_waitcnt vmcnt(3)
	ds_write_b128 v151, v[134:137] offset:34816
	s_waitcnt vmcnt(2)
	ds_write_b128 v151, v[138:141] offset:43520
	s_waitcnt vmcnt(1)
	ds_write_b128 v151, v[142:145] offset:52224
	s_waitcnt vmcnt(0)
	ds_write_b128 v151, v[146:149] offset:60928
	s_and_saveexec_b64 s[2:3], s[16:17]
	s_cbranch_execz .LBB0_1389
	v_mad_u64_u32 v[2:3], s[36:37], v126, s73, v[106:107]
	global_load_dwordx4 v[34:37], v[2:3], off offset:1824
